# per-cluster s_setprio 1/0 around the QK and PV MFMA clusters of the attention block loop; on top of shw_gemm DPP reduction
# speedup vs baseline: 1.0027x; 1.0027x over previous
.LBB0_990:
	v_cmp_lt_f32_e32 vcc, s67, v168
	s_and_b64 vcc, s[10:11], vcc
	v_add_u32_e32 v187, s40, v171
	v_cndmask_b32_e32 v173, v165, v168, vcc
	v_sub_f32_e32 v70, v70, v173
	v_exp_f32_e32 v174, v70
	v_sub_f32_e32 v70, v71, v173
	v_exp_f32_e32 v175, v70
	v_sub_f32_e32 v70, v72, v173
	v_exp_f32_e32 v176, v70
	v_sub_f32_e32 v70, v73, v173
	v_exp_f32_e32 v177, v70
	v_sub_f32_e32 v70, v74, v173
	v_exp_f32_e32 v178, v70
	v_sub_f32_e32 v70, v75, v173
	v_exp_f32_e32 v179, v70
	v_sub_f32_e32 v70, v76, v173
	v_sub_f32_e32 v66, v66, v173
	v_sub_f32_e32 v67, v67, v173
	v_exp_f32_e32 v180, v70
	v_sub_f32_e32 v70, v77, v173
	v_exp_f32_e32 v66, v66
	v_exp_f32_e32 v67, v67
	v_sub_f32_e32 v68, v68, v173
	v_sub_f32_e32 v69, v69, v173
	v_exp_f32_e32 v181, v70
	v_sub_f32_e32 v70, v78, v173
	v_exp_f32_e32 v68, v68
	v_exp_f32_e32 v69, v69
	v_exp_f32_e32 v182, v70
	v_sub_f32_e32 v70, v79, v173
	v_exp_f32_e32 v183, v70
	v_sub_f32_e32 v70, v80, v173
	v_exp_f32_e32 v184, v70
	v_sub_f32_e32 v70, v81, v173
	v_exp_f32_e32 v185, v70
	v_pk_add_f32 v[70:71], v[66:67], 0 op_sel_hi:[1,0]
	v_cvt_pk_bf16_f32 v66, v66, v67
	v_pk_add_f32 v[70:71], v[68:69], v[70:71]
	v_cvt_pk_bf16_f32 v67, v68, v69
	v_pk_add_f32 v[70:71], v[174:175], v[70:71]
	v_cvt_pk_bf16_f32 v68, v174, v175
	v_pk_add_f32 v[70:71], v[176:177], v[70:71]
	v_cvt_pk_bf16_f32 v69, v176, v177
	v_pk_add_f32 v[70:71], v[178:179], v[70:71]
	s_xor_b64 s[0:1], s[22:23], -1
	v_pk_add_f32 v[70:71], v[180:181], v[70:71]
	s_mov_b32 s41, 1
	v_pk_add_f32 v[70:71], v[182:183], v[70:71]
	s_andn2_b64 vcc, exec, s[0:1]
	v_pk_add_f32 v[70:71], v[184:185], v[70:71]
	s_mov_b64 s[22:23], 0
	v_add_f32_e32 v173, v70, v71
	v_mov_b32_e32 v186, v173
	s_nop 1
	v_permlane32_swap_b32 v186, v173
	s_nop 1
	ds_read_b64_tr_b16 v[70:71], v187 offset:34816
	ds_read_b64_tr_b16 v[72:73], v187 offset:36992
	ds_read_b64_tr_b16 v[74:75], v187 offset:34880
	ds_read_b64_tr_b16 v[78:79], v187 offset:34944
	ds_read_b64_tr_b16 v[174:175], v187 offset:35008
	ds_read_b64_tr_b16 v[76:77], v187 offset:37056
	ds_read_b64_tr_b16 v[80:81], v187 offset:37120
	ds_read_b64_tr_b16 v[176:177], v187 offset:37184
	s_waitcnt lgkmcnt(6)
	s_setprio 1
	v_mfma_f32_32x32x16_bf16 v[50:65], v[70:73], v[66:69], v[50:65]
	ds_read_b64_tr_b16 v[70:71], v187 offset:39168
	ds_read_b64_tr_b16 v[72:73], v187 offset:41344
	s_waitcnt lgkmcnt(4)
	v_mfma_f32_32x32x16_bf16 v[34:49], v[74:77], v[66:69], v[34:49]
	s_waitcnt lgkmcnt(3)
	v_mfma_f32_32x32x16_bf16 v[18:33], v[78:81], v[66:69], v[18:33]
	s_waitcnt lgkmcnt(2)
	v_mfma_f32_32x32x16_bf16 v[2:17], v[174:177], v[66:69], v[2:17]
	ds_read_b64_tr_b16 v[74:75], v187 offset:39232
	ds_read_b64_tr_b16 v[78:79], v187 offset:39296
	ds_read_b64_tr_b16 v[174:175], v187 offset:39360
	ds_read_b64_tr_b16 v[76:77], v187 offset:41408
	ds_read_b64_tr_b16 v[80:81], v187 offset:41472
	ds_read_b64_tr_b16 v[176:177], v187 offset:41536
	v_cvt_pk_bf16_f32 v66, v178, v179
	v_cvt_pk_bf16_f32 v67, v180, v181
	v_cvt_pk_bf16_f32 v68, v182, v183
	v_cvt_pk_bf16_f32 v69, v184, v185
	s_waitcnt lgkmcnt(6)
	s_nop 0
	v_mfma_f32_32x32x16_bf16 v[50:65], v[70:73], v[66:69], v[50:65]
	v_add_f32_e32 v70, v186, v173
	v_add_f32_e32 v137, v137, v70
	s_waitcnt lgkmcnt(2)
	v_mfma_f32_32x32x16_bf16 v[34:49], v[74:77], v[66:69], v[34:49]
	s_waitcnt lgkmcnt(1)
	v_mfma_f32_32x32x16_bf16 v[18:33], v[78:81], v[66:69], v[18:33]
	s_waitcnt lgkmcnt(0)
	v_mfma_f32_32x32x16_bf16 v[2:17], v[174:177], v[66:69], v[2:17]
	s_setprio 0
	s_cbranch_vccz .LBB0_981
.LBB0_991:
	s_mul_i32 s40, s41, 0x2200
	v_add_u32_e32 v173, s40, v172
	ds_read_b128 v[66:69], v173
	ds_read_b128 v[174:177], v173 offset:32
	ds_read_b128 v[178:181], v173 offset:64
	ds_read_b128 v[182:185], v173 offset:96
	s_waitcnt lgkmcnt(3)
	s_setprio 1
	v_mfma_f32_32x32x16_bf16 v[66:81], v[66:69], v[82:85], 0
	s_waitcnt lgkmcnt(2)
	v_mfma_f32_32x32x16_bf16 v[66:81], v[174:177], v[86:89], v[66:81]
	s_waitcnt lgkmcnt(1)
	v_mfma_f32_32x32x16_bf16 v[66:81], v[178:181], v[90:93], v[66:81]
	s_waitcnt lgkmcnt(0)
	v_mfma_f32_32x32x16_bf16 v[66:81], v[182:185], v[94:97], v[66:81]
	ds_read_b128 v[174:177], v173 offset:128
	ds_read_b128 v[178:181], v173 offset:160
	ds_read_b128 v[182:185], v173 offset:192
	ds_read_b128 v[186:189], v173 offset:224
	s_waitcnt lgkmcnt(3)
	v_mfma_f32_32x32x16_bf16 v[66:81], v[174:177], v[98:101], v[66:81]
	s_waitcnt lgkmcnt(2)
	v_mfma_f32_32x32x16_bf16 v[66:81], v[178:181], v[102:105], v[66:81]
	s_waitcnt lgkmcnt(1)
	v_mfma_f32_32x32x16_bf16 v[66:81], v[182:185], v[106:109], v[66:81]
	s_waitcnt lgkmcnt(0)
	v_mfma_f32_32x32x16_bf16 v[66:81], v[186:189], v[110:113], v[66:81]
	s_setprio 0
	s_and_b64 vcc, exec, s[24:25]
	s_mov_b64 s[0:1], -1
	s_cbranch_vccz .LBB0_993
	s_nop 8
	v_max_f32_e32 v173, v69, v69
	v_max_f32_e32 v174, v68, v68
	v_max_f32_e32 v173, v174, v173
	v_max_f32_e32 v174, v73, v73
	v_max_f32_e32 v175, v72, v72
	v_max_f32_e32 v174, v175, v174
	v_max_f32_e32 v175, v75, v75
	v_max_f32_e32 v176, v74, v74
	v_max_f32_e32 v175, v176, v175
	v_max_f32_e32 v176, v77, v77
	v_max_f32_e32 v177, v76, v76
	v_max_f32_e32 v176, v177, v176
	v_max_f32_e32 v177, v81, v81
	v_max_f32_e32 v178, v80, v80
	v_max_f32_e32 v177, v178, v177
	v_max3_f32 v177, v78, v79, v177
	v_max3_f32 v173, v66, v67, v173
	v_max3_f32 v174, v70, v71, v174
	v_max3_f32 v175, v175, v176, v177
	v_max3_f32 v173, v173, v174, v175
	s_mov_b64 s[0:1], 0
